# up-GEMM k-loop load segments: DMA issue interleaved with the fragment ds_reads (DMA first), on top of 4/4/4/4 staging + SGPR-base DMA addressing
# speedup vs baseline: 1.0037x; 1.0001x over previous
; #define PG8_STAGE(bufoff, gbase, voff) do { _Pragma("unroll") for (int _i = 0; _i < 2; ++_i) \
;         __builtin_amdgcn_global_load_lds((const unsigned*)((const char*)(gbase) + (voff)[_i]), (LAS unsigned*)(lds + (bufoff) + ldsw + _i * 8192), 16, 0, 0); } while (0)
; #define PG8_LDA(dst, b, h) do { _Pragma("unroll") for (int m = 0; m < 4; ++m) _Pragma("unroll") for (int k = 0; k < 2; ++k) dst[m][k] = *(const LAS bf16x8*)(lds + PG8_SA(b, h) + aoff + m * 2048 + k * 1024); } while (0)
; #define PG8_LDB(dst, b, h) do { _Pragma("unroll") for (int n = 0; n < 2; ++n) _Pragma("unroll") for (int k = 0; k < 2; ++k) dst[n][k] = *(const LAS bf16x8*)(lds + PG8_SB(b, h) + boff + n * 2048 + k * 1024); } while (0)
; #define PG8_MMA(ai, bj, At, Bt) do { __builtin_amdgcn_s_setprio(1); _Pragma("unroll") for (int m = 0; m < 4; ++m) _Pragma("unroll") for (int n = 0; n < 2; ++n) _Pragma("unroll") for (int k = 0; k < 2; ++k) \
;         acc[ai][bj][m][n] = __builtin_amdgcn_mfma_f32_16x16x32_bf16(Bt[n][k], At[m][k], acc[ai][bj][m][n], 0, 0, 0); __builtin_amdgcn_s_setprio(0); } while (0)
; #define PG8_WAIT_V(n) asm volatile("s_waitcnt vmcnt(" #n ")" ::: "memory")
; #define PG8_WAIT_L(n) asm volatile("s_waitcnt lgkmcnt(" #n ")" ::: "memory")
; #define PG8_BAR __builtin_amdgcn_s_barrier()
; template <class Epi, class Sched, bool ALIGN_EPI = false, bool SP2 = false>
; __device__ __forceinline__ void gemm_phase(LAS unsigned char* lds, const Gemm g, const Sched& S, const Epi& E, int wid) {
;     ...
;         for (int t = 0; t < nt; t += 2) {
;             const bool last = (t == nt - 2);
;             const char* a1 = cA + (size_t)(t + 1) * kstep;
;             const char* a2 = last ? nA : cA + (size_t)(t + 2) * kstep; const char* b2 = last ? nB : cB + (size_t)(t + 2) * kstep;
;             const char* a3 = a2 + kstep; const char* b3 = b2 + kstep;
;             if constexpr (SP2) {
;             PG8_LDB(B0, 0, 0); PG8_LDB(B1, 0, 1); PG8_SCHED; PG8_LDA(At, 0, 0); PG8_STAGE(PG8_SA(1, 1), a1 + hstepA, voffA);
;             PG8_WAIT_V(8); PG8_WAIT_L(0); PG8_BAR; PG8_MMA(0, 0, At, B0); PG8_MMA(0, 1, At, B1); PG8_BAR; PG8_SCHED;
;             PG8_LDA(At, 0, 1); PG8_STAGE(PG8_SB(0, 0), b2, voffB); PG8_STAGE(PG8_SB(0, 1), b2 + hstepB, voffB); PG8_STAGE(PG8_SA(0, 0), a2, voffA);
;             PG8_WAIT_V(8); PG8_WAIT_L(0); PG8_BAR; PG8_MMA(1, 0, At, B0); PG8_MMA(1, 1, At, B1); PG8_BAR; PG8_SCHED;
.LBB0_968:
	s_add_u32 s56, s54, 0x100
	s_addc_u32 s57, s55, 0
	s_add_i32 s62, 0, 0x10000
	s_cmp_eq_u32 s93, 28
	s_cselect_b32 s49, s41, s57
	s_cselect_b32 s48, s42, s56
	s_cselect_b32 vcc_hi, s43, s61
	s_cselect_b32 vcc_lo, s59, s60
	s_add_i32 s63, 0, 0x14000
	v_add_u32_e32 v116, s62, v228
	v_add_u32_e32 v132, s63, v228
	s_add_i32 m0, s79, 0xc000
	s_add_u32 s100, s54, 0x80
	s_addc_u32 s101, s55, 0
	s_mov_b32 m0, s94
	s_nop 0
	global_load_lds_dwordx4 v176, s[100:101]
	ds_read_b128 v[104:107], v116
	ds_read_b128 v[108:111], v116 offset:1024
	ds_read_b128 v[112:115], v116 offset:2048
	ds_read_b128 v[116:119], v116 offset:3072
	s_mov_b32 m0, s95
	s_nop 0
	global_load_lds_dwordx4 v174, s[100:101]
	ds_read_b128 v[120:123], v132
	ds_read_b128 v[124:127], v132 offset:1024
	ds_read_b128 v[128:131], v132 offset:2048
	ds_read_b128 v[132:135], v132 offset:3072
	s_add_u32 s100, s100, 0x80000
	s_addc_u32 s101, s101, 0
	s_add_i32 m0, s79, 0xc000
	s_nop 0
	global_load_lds_dwordx4 v176, s[100:101]
	ds_read_b128 v[144:147], v231
	ds_read_b128 v[164:167], v231 offset:1024
	ds_read_b128 v[168:171], v231 offset:2048
	ds_read_b128 v[186:189], v231 offset:3072
	s_add_i32 m0, s79, 0xe000
	s_nop 0
	global_load_lds_dwordx4 v174, s[100:101]
	ds_read_b128 v[200:203], v231 offset:4096
	ds_read_b128 v[204:207], v231 offset:5120
	ds_read_b128 v[208:211], v231 offset:6144
	ds_read_b128 v[212:215], v231 offset:7168
	s_waitcnt vmcnt(8)
	s_waitcnt lgkmcnt(0)
	s_barrier
	s_setprio 1
	s_waitcnt lgkmcnt(0)
	v_mfma_f32_16x16x32_bf16 v[160:163], v[104:107], v[144:147], v[160:163]
	v_mfma_f32_16x16x32_bf16 v[60:63], v[112:115], v[144:147], v[60:63]
	v_mfma_f32_16x16x32_bf16 v[152:155], v[104:107], v[168:171], v[152:155]
	v_mfma_f32_16x16x32_bf16 v[36:39], v[112:115], v[168:171], v[36:39]
	v_mfma_f32_16x16x32_bf16 v[140:143], v[104:107], v[200:203], v[140:143]
	v_mfma_f32_16x16x32_bf16 v[56:59], v[112:115], v[200:203], v[56:59]
	v_mfma_f32_16x16x32_bf16 v[100:103], v[104:107], v[208:211], v[100:103]
	v_mfma_f32_16x16x32_bf16 v[48:51], v[112:115], v[208:211], v[48:51]
	v_mfma_f32_16x16x32_bf16 v[160:163], v[108:111], v[164:167], v[160:163]
	v_mfma_f32_16x16x32_bf16 v[60:63], v[116:119], v[164:167], v[60:63]
	v_mfma_f32_16x16x32_bf16 v[152:155], v[108:111], v[186:189], v[152:155]
	v_mfma_f32_16x16x32_bf16 v[36:39], v[116:119], v[186:189], v[36:39]
	v_mfma_f32_16x16x32_bf16 v[140:143], v[108:111], v[204:207], v[140:143]
	v_mfma_f32_16x16x32_bf16 v[56:59], v[116:119], v[204:207], v[56:59]
	v_mfma_f32_16x16x32_bf16 v[100:103], v[108:111], v[212:215], v[100:103]
	v_mfma_f32_16x16x32_bf16 v[48:51], v[116:119], v[212:215], v[48:51]
	s_setprio 0
	s_setprio 1
	v_mfma_f32_16x16x32_bf16 v[156:159], v[120:123], v[144:147], v[156:159]
	v_mfma_f32_16x16x32_bf16 v[52:55], v[128:131], v[144:147], v[52:55]
	v_mfma_f32_16x16x32_bf16 v[32:35], v[128:131], v[168:171], v[32:35]
	v_mfma_f32_16x16x32_bf16 v[136:139], v[120:123], v[200:203], v[136:139]
	v_mfma_f32_16x16x32_bf16 v[44:47], v[128:131], v[200:203], v[44:47]
	v_mfma_f32_16x16x32_bf16 v[96:99], v[120:123], v[208:211], v[96:99]
	v_mfma_f32_16x16x32_bf16 v[40:43], v[128:131], v[208:211], v[40:43]
	v_mfma_f32_16x16x32_bf16 v[156:159], v[124:127], v[164:167], v[156:159]
	v_mfma_f32_16x16x32_bf16 v[52:55], v[132:135], v[164:167], v[52:55]
	v_mfma_f32_16x16x32_bf16 v[144:147], v[120:123], v[168:171], v[148:151]
	v_mfma_f32_16x16x32_bf16 v[32:35], v[132:135], v[186:189], v[32:35]
	v_mfma_f32_16x16x32_bf16 v[136:139], v[124:127], v[204:207], v[136:139]
	v_mfma_f32_16x16x32_bf16 v[44:47], v[132:135], v[204:207], v[44:47]
	v_mfma_f32_16x16x32_bf16 v[96:99], v[124:127], v[212:215], v[96:99]
	v_mfma_f32_16x16x32_bf16 v[40:43], v[132:135], v[212:215], v[40:43]
	v_mfma_f32_16x16x32_bf16 v[144:147], v[124:127], v[186:189], v[144:147]
	s_setprio 0
	s_barrier
	s_add_i32 s54, s62, s89
	s_mov_b64 s[100:101], vcc
	s_mov_b32 m0, s54
	s_nop 0
	global_load_lds_dwordx4 v192, s[100:101]
	ds_read_b128 v[148:151], v231 offset:16384
	ds_read_b128 v[164:167], v231 offset:17408
	s_add_i32 m0, s54, 0x2000
	s_add_u32 s54, vcc_lo, 0x80000
	s_addc_u32 s55, vcc_hi, 0
	s_add_i32 s62, s63, s89
	global_load_lds_dwordx4 v172, s[100:101]
	ds_read_b128 v[168:171], v231 offset:18432
	ds_read_b128 v[186:189], v231 offset:19456
	s_mov_b32 m0, s62
	s_nop 0
	global_load_lds_dwordx4 v192, s[54:55]
	ds_read_b128 v[200:203], v231 offset:20480
	ds_read_b128 v[204:207], v231 offset:21504
	s_add_i32 m0, s62, 0x2000
	s_nop 0
	global_load_lds_dwordx4 v172, s[54:55]
	ds_read_b128 v[208:211], v231 offset:22528
	ds_read_b128 v[212:215], v231 offset:23552
	s_waitcnt vmcnt(6)
	s_waitcnt lgkmcnt(0)
	s_barrier
; #define PG8_STAGE(bufoff, gbase, voff) do { _Pragma("unroll") for (int _i = 0; _i < 2; ++_i) \
;         __builtin_amdgcn_global_load_lds((const unsigned*)((const char*)(gbase) + (voff)[_i]), (LAS unsigned*)(lds + (bufoff) + ldsw + _i * 8192), 16, 0, 0); } while (0)
; #define PG8_LDA(dst, b, h) do { _Pragma("unroll") for (int m = 0; m < 4; ++m) _Pragma("unroll") for (int k = 0; k < 2; ++k) dst[m][k] = *(const LAS bf16x8*)(lds + PG8_SA(b, h) + aoff + m * 2048 + k * 1024); } while (0)
; #define PG8_LDB(dst, b, h) do { _Pragma("unroll") for (int n = 0; n < 2; ++n) _Pragma("unroll") for (int k = 0; k < 2; ++k) dst[n][k] = *(const LAS bf16x8*)(lds + PG8_SB(b, h) + boff + n * 2048 + k * 1024); } while (0)
; #define PG8_MMA(ai, bj, At, Bt) do { __builtin_amdgcn_s_setprio(1); _Pragma("unroll") for (int m = 0; m < 4; ++m) _Pragma("unroll") for (int n = 0; n < 2; ++n) _Pragma("unroll") for (int k = 0; k < 2; ++k) \
;         acc[ai][bj][m][n] = __builtin_amdgcn_mfma_f32_16x16x32_bf16(Bt[n][k], At[m][k], acc[ai][bj][m][n], 0, 0, 0); __builtin_amdgcn_s_setprio(0); } while (0)
; #define PG8_WAIT_V(n) asm volatile("s_waitcnt vmcnt(" #n ")" ::: "memory")
; #define PG8_WAIT_L(n) asm volatile("s_waitcnt lgkmcnt(" #n ")" ::: "memory")
; #define PG8_BAR __builtin_amdgcn_s_barrier()
; #define PG8_SCHED __builtin_amdgcn_sched_barrier(0)
; template <class Epi, class Sched, bool ALIGN_EPI = false, bool SP2 = false>
; __device__ __forceinline__ void gemm_phase(LAS unsigned char* lds, const Gemm g, const Sched& S, const Epi& E, int wid) {
;     ...
;             PG8_WAIT_V(8); PG8_WAIT_L(0); PG8_BAR; PG8_MMA(0, 0, At, B0); PG8_MMA(0, 1, At, B1); PG8_BAR; PG8_SCHED;
;             PG8_LDA(At, 0, 1); PG8_STAGE(PG8_SB(0, 0), b2, voffB); PG8_STAGE(PG8_SB(0, 1), b2 + hstepB, voffB); PG8_STAGE(PG8_SA(0, 0), a2, voffA);
;             PG8_WAIT_V(8); PG8_WAIT_L(0); PG8_BAR; PG8_MMA(1, 0, At, B0); PG8_MMA(1, 1, At, B1); PG8_BAR; PG8_SCHED;
;             PG8_LDB(B0, 1, 0); PG8_LDB(B1, 1, 1); PG8_SCHED; PG8_LDA(At, 1, 0); PG8_STAGE(PG8_SA(0, 1), a2 + hstepA, voffA);
;             PG8_WAIT_V(8); PG8_WAIT_L(0); PG8_BAR; PG8_MMA(0, 0, At, B0); PG8_MMA(0, 1, At, B1); PG8_BAR; PG8_SCHED;
;             PG8_LDA(At, 1, 1); PG8_STAGE(PG8_SB(1, 0), b3, voffB); PG8_STAGE(PG8_SB(1, 1), b3 + hstepB, voffB); PG8_STAGE(PG8_SA(1, 0), a3, voffA);
	s_setprio 1
	s_waitcnt lgkmcnt(0)
	v_mfma_f32_16x16x32_bf16 v[92:95], v[104:107], v[148:151], v[92:95]
	v_mfma_f32_16x16x32_bf16 v[28:31], v[112:115], v[148:151], v[28:31]
	v_mfma_f32_16x16x32_bf16 v[88:91], v[104:107], v[168:171], v[88:91]
	v_mfma_f32_16x16x32_bf16 v[4:7], v[112:115], v[168:171], v[4:7]
	v_mfma_f32_16x16x32_bf16 v[80:83], v[104:107], v[200:203], v[80:83]
	v_mfma_f32_16x16x32_bf16 v[24:27], v[112:115], v[200:203], v[24:27]
	v_mfma_f32_16x16x32_bf16 v[72:75], v[104:107], v[208:211], v[72:75]
	v_mfma_f32_16x16x32_bf16 v[16:19], v[112:115], v[208:211], v[16:19]
	v_mfma_f32_16x16x32_bf16 v[92:95], v[108:111], v[164:167], v[92:95]
	v_mfma_f32_16x16x32_bf16 v[28:31], v[116:119], v[164:167], v[28:31]
	v_mfma_f32_16x16x32_bf16 v[88:91], v[108:111], v[186:189], v[88:91]
	v_mfma_f32_16x16x32_bf16 v[4:7], v[116:119], v[186:189], v[4:7]
	v_mfma_f32_16x16x32_bf16 v[80:83], v[108:111], v[204:207], v[80:83]
	v_mfma_f32_16x16x32_bf16 v[24:27], v[116:119], v[204:207], v[24:27]
	v_mfma_f32_16x16x32_bf16 v[72:75], v[108:111], v[212:215], v[72:75]
	v_mfma_f32_16x16x32_bf16 v[16:19], v[116:119], v[212:215], v[16:19]
	s_setprio 0
	s_setprio 1
	v_mfma_f32_16x16x32_bf16 v[84:87], v[120:123], v[148:151], v[84:87]
	v_mfma_f32_16x16x32_bf16 v[20:23], v[128:131], v[148:151], v[20:23]
	v_mfma_f32_16x16x32_bf16 v[76:79], v[120:123], v[168:171], v[76:79]
	v_mfma_f32_16x16x32_bf16 v[0:3], v[128:131], v[168:171], v[0:3]
	v_mfma_f32_16x16x32_bf16 v[68:71], v[120:123], v[200:203], v[68:71]
	v_mfma_f32_16x16x32_bf16 v[12:15], v[128:131], v[200:203], v[12:15]
	v_mfma_f32_16x16x32_bf16 v[64:67], v[120:123], v[208:211], v[64:67]
	v_mfma_f32_16x16x32_bf16 v[8:11], v[128:131], v[208:211], v[8:11]
	v_mfma_f32_16x16x32_bf16 v[84:87], v[124:127], v[164:167], v[84:87]
	v_mfma_f32_16x16x32_bf16 v[20:23], v[132:135], v[164:167], v[20:23]
	v_mfma_f32_16x16x32_bf16 v[76:79], v[124:127], v[186:189], v[76:79]
	v_mfma_f32_16x16x32_bf16 v[0:3], v[132:135], v[186:189], v[0:3]
	v_mfma_f32_16x16x32_bf16 v[68:71], v[124:127], v[204:207], v[68:71]
	v_mfma_f32_16x16x32_bf16 v[12:15], v[132:135], v[204:207], v[12:15]
	v_mfma_f32_16x16x32_bf16 v[64:67], v[124:127], v[212:215], v[64:67]
	v_mfma_f32_16x16x32_bf16 v[8:11], v[132:135], v[212:215], v[8:11]
	s_setprio 0
	s_barrier
	s_add_i32 s54, 0, 0x18000
	s_add_i32 s55, 0, 0x1c000
	v_add_u32_e32 v116, s54, v228
	v_add_u32_e32 v132, s55, v228
	s_add_u32 s48, s48, 0x80000
	s_addc_u32 s49, s49, 0
	s_mov_b32 m0, s77
	s_add_u32 s100, s48, 0xfff80000
	s_addc_u32 s101, s49, -1
	s_mov_b32 m0, s79
	s_nop 0
	global_load_lds_dwordx4 v176, s[100:101]
	ds_read_b128 v[104:107], v116
	ds_read_b128 v[108:111], v116 offset:1024
	ds_read_b128 v[112:115], v116 offset:2048
	ds_read_b128 v[116:119], v116 offset:3072
	s_mov_b32 m0, s81
	s_nop 0
	global_load_lds_dwordx4 v174, s[100:101]
	ds_read_b128 v[120:123], v132
	ds_read_b128 v[124:127], v132 offset:1024
	ds_read_b128 v[128:131], v132 offset:2048
	ds_read_b128 v[132:135], v132 offset:3072
	s_mov_b32 m0, s77
	s_nop 0
	global_load_lds_dwordx4 v176, s[48:49]
	ds_read_b128 v[148:151], v231 offset:32768
	ds_read_b128 v[164:167], v231 offset:33792
	ds_read_b128 v[168:171], v231 offset:34816
	ds_read_b128 v[186:189], v231 offset:35840
	s_mov_b32 m0, s4
	s_nop 0
	global_load_lds_dwordx4 v174, s[48:49]
	ds_read_b128 v[200:203], v231 offset:36864
	ds_read_b128 v[204:207], v231 offset:37888
	ds_read_b128 v[208:211], v231 offset:38912
	ds_read_b128 v[212:215], v231 offset:39936
	s_waitcnt vmcnt(8)
	s_waitcnt lgkmcnt(0)
	s_barrier
; #define PG8_STAGE(bufoff, gbase, voff) do { _Pragma("unroll") for (int _i = 0; _i < 2; ++_i) \
;         __builtin_amdgcn_global_load_lds((const unsigned*)((const char*)(gbase) + (voff)[_i]), (LAS unsigned*)(lds + (bufoff) + ldsw + _i * 8192), 16, 0, 0); } while (0)
; #define PG8_LDA(dst, b, h) do { _Pragma("unroll") for (int m = 0; m < 4; ++m) _Pragma("unroll") for (int k = 0; k < 2; ++k) dst[m][k] = *(const LAS bf16x8*)(lds + PG8_SA(b, h) + aoff + m * 2048 + k * 1024); } while (0)
; #define PG8_LDB(dst, b, h) do { _Pragma("unroll") for (int n = 0; n < 2; ++n) _Pragma("unroll") for (int k = 0; k < 2; ++k) dst[n][k] = *(const LAS bf16x8*)(lds + PG8_SB(b, h) + boff + n * 2048 + k * 1024); } while (0)
; #define PG8_MMA(ai, bj, At, Bt) do { __builtin_amdgcn_s_setprio(1); _Pragma("unroll") for (int m = 0; m < 4; ++m) _Pragma("unroll") for (int n = 0; n < 2; ++n) _Pragma("unroll") for (int k = 0; k < 2; ++k) \
;         acc[ai][bj][m][n] = __builtin_amdgcn_mfma_f32_16x16x32_bf16(Bt[n][k], At[m][k], acc[ai][bj][m][n], 0, 0, 0); __builtin_amdgcn_s_setprio(0); } while (0)
; #define PG8_WAIT_V(n) asm volatile("s_waitcnt vmcnt(" #n ")" ::: "memory")
; #define PG8_WAIT_L(n) asm volatile("s_waitcnt lgkmcnt(" #n ")" ::: "memory")
; #define PG8_BAR __builtin_amdgcn_s_barrier()
; #define PG8_SCHED __builtin_amdgcn_sched_barrier(0)
; template <class Epi, class Sched, bool ALIGN_EPI = false, bool SP2 = false>
; __device__ __forceinline__ void gemm_phase(LAS unsigned char* lds, const Gemm g, const Sched& S, const Epi& E, int wid) {
;     ...
;         for (int t = 0; t < nt; t += 2) {
;             const bool last = (t == nt - 2);
;             const char* a1 = cA + (size_t)(t + 1) * kstep;
;             const char* a2 = last ? nA : cA + (size_t)(t + 2) * kstep; const char* b2 = last ? nB : cB + (size_t)(t + 2) * kstep;
;     ...
;             PG8_LDB(B0, 1, 0); PG8_LDB(B1, 1, 1); PG8_SCHED; PG8_LDA(At, 1, 0); PG8_STAGE(PG8_SA(0, 1), a2 + hstepA, voffA);
;             PG8_WAIT_V(8); PG8_WAIT_L(0); PG8_BAR; PG8_MMA(0, 0, At, B0); PG8_MMA(0, 1, At, B1); PG8_BAR; PG8_SCHED;
;             PG8_LDA(At, 1, 1); PG8_STAGE(PG8_SB(1, 0), b3, voffB); PG8_STAGE(PG8_SB(1, 1), b3 + hstepB, voffB); PG8_STAGE(PG8_SA(1, 0), a3, voffA);
;             PG8_WAIT_V(8); PG8_WAIT_L(0); PG8_BAR; PG8_MMA(1, 0, At, B0); PG8_MMA(1, 1, At, B1); PG8_BAR; PG8_SCHED;
	s_setprio 1
	s_waitcnt lgkmcnt(0)
	v_mfma_f32_16x16x32_bf16 v[160:163], v[104:107], v[148:151], v[160:163]
	v_mfma_f32_16x16x32_bf16 v[60:63], v[112:115], v[148:151], v[60:63]
	v_mfma_f32_16x16x32_bf16 v[152:155], v[104:107], v[168:171], v[152:155]
	v_mfma_f32_16x16x32_bf16 v[36:39], v[112:115], v[168:171], v[36:39]
	v_mfma_f32_16x16x32_bf16 v[140:143], v[104:107], v[200:203], v[140:143]
	v_mfma_f32_16x16x32_bf16 v[56:59], v[112:115], v[200:203], v[56:59]
	v_mfma_f32_16x16x32_bf16 v[100:103], v[104:107], v[208:211], v[100:103]
	v_mfma_f32_16x16x32_bf16 v[48:51], v[112:115], v[208:211], v[48:51]
	v_mfma_f32_16x16x32_bf16 v[160:163], v[108:111], v[164:167], v[160:163]
	v_mfma_f32_16x16x32_bf16 v[60:63], v[116:119], v[164:167], v[60:63]
	v_mfma_f32_16x16x32_bf16 v[152:155], v[108:111], v[186:189], v[152:155]
	v_mfma_f32_16x16x32_bf16 v[36:39], v[116:119], v[186:189], v[36:39]
	v_mfma_f32_16x16x32_bf16 v[140:143], v[108:111], v[204:207], v[140:143]
	v_mfma_f32_16x16x32_bf16 v[56:59], v[116:119], v[204:207], v[56:59]
	v_mfma_f32_16x16x32_bf16 v[100:103], v[108:111], v[212:215], v[100:103]
	v_mfma_f32_16x16x32_bf16 v[48:51], v[116:119], v[212:215], v[48:51]
	s_setprio 0
	s_setprio 1
	v_mfma_f32_16x16x32_bf16 v[156:159], v[120:123], v[148:151], v[156:159]
	v_mfma_f32_16x16x32_bf16 v[52:55], v[128:131], v[148:151], v[52:55]
	v_mfma_f32_16x16x32_bf16 v[144:147], v[120:123], v[168:171], v[144:147]
	v_mfma_f32_16x16x32_bf16 v[32:35], v[128:131], v[168:171], v[32:35]
	v_mfma_f32_16x16x32_bf16 v[136:139], v[120:123], v[200:203], v[136:139]
	v_mfma_f32_16x16x32_bf16 v[44:47], v[128:131], v[200:203], v[44:47]
	v_mfma_f32_16x16x32_bf16 v[96:99], v[120:123], v[208:211], v[96:99]
	v_mfma_f32_16x16x32_bf16 v[40:43], v[128:131], v[208:211], v[40:43]
	v_mfma_f32_16x16x32_bf16 v[156:159], v[124:127], v[164:167], v[156:159]
	v_mfma_f32_16x16x32_bf16 v[52:55], v[132:135], v[164:167], v[52:55]
	v_mfma_f32_16x16x32_bf16 v[148:151], v[124:127], v[186:189], v[144:147]
	v_mfma_f32_16x16x32_bf16 v[32:35], v[132:135], v[186:189], v[32:35]
	v_mfma_f32_16x16x32_bf16 v[136:139], v[124:127], v[204:207], v[136:139]
	v_mfma_f32_16x16x32_bf16 v[44:47], v[132:135], v[204:207], v[44:47]
	v_mfma_f32_16x16x32_bf16 v[96:99], v[124:127], v[212:215], v[96:99]
	v_mfma_f32_16x16x32_bf16 v[40:43], v[132:135], v[212:215], v[40:43]
	s_setprio 0
	s_barrier
	s_add_i32 s48, s54, s89
	s_add_u32 s100, vcc_lo, 0x80
	s_addc_u32 s101, vcc_hi, 0
	s_mov_b32 m0, s48
	s_nop 0
	global_load_lds_dwordx4 v192, s[100:101]
	ds_read_b128 v[144:147], v231 offset:49152
	ds_read_b128 v[164:167], v231 offset:50176
	s_add_i32 m0, s48, 0x2000
	s_add_u32 s48, vcc_lo, 0x80080
	s_addc_u32 s49, vcc_hi, 0
	s_add_i32 s54, s55, s89
	global_load_lds_dwordx4 v172, s[100:101]
	ds_read_b128 v[168:171], v231 offset:51200
	ds_read_b128 v[186:189], v231 offset:52224
	s_mov_b32 m0, s54
	s_nop 0
	global_load_lds_dwordx4 v192, s[48:49]
	ds_read_b128 v[200:203], v231 offset:53248
	ds_read_b128 v[204:207], v231 offset:54272
	s_add_i32 m0, s54, 0x2000
	s_nop 0
	global_load_lds_dwordx4 v172, s[48:49]
	ds_read_b128 v[208:211], v231 offset:55296
	ds_read_b128 v[212:215], v231 offset:56320
	s_waitcnt vmcnt(6)
	s_waitcnt lgkmcnt(0)
	s_barrier
	s_setprio 1
	s_waitcnt lgkmcnt(0)
	v_mfma_f32_16x16x32_bf16 v[92:95], v[104:107], v[144:147], v[92:95]
	v_mfma_f32_16x16x32_bf16 v[28:31], v[112:115], v[144:147], v[28:31]
	v_mfma_f32_16x16x32_bf16 v[88:91], v[104:107], v[168:171], v[88:91]
	v_mfma_f32_16x16x32_bf16 v[4:7], v[112:115], v[168:171], v[4:7]
	v_mfma_f32_16x16x32_bf16 v[80:83], v[104:107], v[200:203], v[80:83]
	v_mfma_f32_16x16x32_bf16 v[24:27], v[112:115], v[200:203], v[24:27]
	v_mfma_f32_16x16x32_bf16 v[72:75], v[104:107], v[208:211], v[72:75]
	v_mfma_f32_16x16x32_bf16 v[16:19], v[112:115], v[208:211], v[16:19]
	v_mfma_f32_16x16x32_bf16 v[92:95], v[108:111], v[164:167], v[92:95]
	v_mfma_f32_16x16x32_bf16 v[28:31], v[116:119], v[164:167], v[28:31]
	v_mfma_f32_16x16x32_bf16 v[88:91], v[108:111], v[186:189], v[88:91]
	v_mfma_f32_16x16x32_bf16 v[4:7], v[116:119], v[186:189], v[4:7]
	v_mfma_f32_16x16x32_bf16 v[80:83], v[108:111], v[204:207], v[80:83]
	v_mfma_f32_16x16x32_bf16 v[24:27], v[116:119], v[204:207], v[24:27]
	v_mfma_f32_16x16x32_bf16 v[72:75], v[108:111], v[212:215], v[72:75]
	v_mfma_f32_16x16x32_bf16 v[16:19], v[116:119], v[212:215], v[16:19]
	s_setprio 0
	s_setprio 1
	v_mfma_f32_16x16x32_bf16 v[84:87], v[120:123], v[144:147], v[84:87]
	v_mfma_f32_16x16x32_bf16 v[20:23], v[128:131], v[144:147], v[20:23]
	v_mfma_f32_16x16x32_bf16 v[76:79], v[120:123], v[168:171], v[76:79]
	v_mfma_f32_16x16x32_bf16 v[0:3], v[128:131], v[168:171], v[0:3]
	v_mfma_f32_16x16x32_bf16 v[68:71], v[120:123], v[200:203], v[68:71]
	v_mfma_f32_16x16x32_bf16 v[12:15], v[128:131], v[200:203], v[12:15]
	v_mfma_f32_16x16x32_bf16 v[64:67], v[120:123], v[208:211], v[64:67]
	v_mfma_f32_16x16x32_bf16 v[8:11], v[128:131], v[208:211], v[8:11]
	v_mfma_f32_16x16x32_bf16 v[84:87], v[124:127], v[164:167], v[84:87]
	v_mfma_f32_16x16x32_bf16 v[20:23], v[132:135], v[164:167], v[20:23]
	v_mfma_f32_16x16x32_bf16 v[76:79], v[124:127], v[186:189], v[76:79]
	v_mfma_f32_16x16x32_bf16 v[0:3], v[132:135], v[186:189], v[0:3]
	v_mfma_f32_16x16x32_bf16 v[68:71], v[124:127], v[204:207], v[68:71]
	v_mfma_f32_16x16x32_bf16 v[12:15], v[132:135], v[204:207], v[12:15]
	v_mfma_f32_16x16x32_bf16 v[64:67], v[124:127], v[212:215], v[64:67]
	v_mfma_f32_16x16x32_bf16 v[8:11], v[132:135], v[212:215], v[8:11]
	s_setprio 0
	s_barrier
	s_add_i32 s93, s93, 2
	s_add_u32 s60, s60, 0x100
	s_addc_u32 s61, s61, 0
	s_cmp_gt_u32 s93, 29
	s_mov_b64 s[54:55], s[56:57]
	s_cbranch_scc0 .LBB0_968
	s_and_b64 vcc, exec, s[82:83]
	s_cbranch_vccz .LBB0_971
	s_barrier
